# norm C pre-loop: row 0's eight x loads issued together (were 8 dependent load->vmcnt(0) round trips through one register pair), unpacked in place behind one wait
# baseline (speedup 1.0000x reference)
; #define GAS __attribute__((address_space(1)))
; DI Frame launder(const Frame& F0) { Frame F = F0; asm volatile("; launder frame" : "+v"(F.tid), "+v"(F.lane), "+s"(F.wave), "+s"(F.vcu)); return F; }
; DI void norm_load_x(f32x4 (&v)[8], const void* xlat, const void* xctx, int xin_bf16, int R, int co) {
;     if (xin_bf16) { const bf16* xr = R < NLAT ? (const bf16*)xlat + (size_t)R * DM : (const bf16*)xctx + (size_t)(R - NLAT) * DM;
;         v2u t[8];
; #pragma unroll
;         for (int j = 0; j < 8; ++j) t[j] = *(const GAS v2u*)(xr + j * 256 + co);
; #pragma unroll
;         for (int j = 0; j < 8; ++j) v[j] = (f32x4){bflo(t[j].x), bfhi(t[j].x), bflo(t[j].y), bfhi(t[j].y)}; }
;     else { const float* xr = R < NLAT ? (const float*)xlat + (size_t)R * DM : (const float*)xctx + (size_t)(R - NLAT) * DM;
; #pragma unroll
;         for (int j = 0; j < 8; ++j) v[j] = *(const GAS f32x4*)(xr + j * 256 + co); }
; }
; DI void phase_norm(const Frame& F0, int nrows, const void* xlat, const void* xctx, int xin_bf16, const bf16* Y, const float* gainY, const float* gate  ,
;                    void* Xout_lat, void* Xout_ctx, int xout_bf16, bf16* Hout, const float* gainH, const float* shift, const float* scale) {
;     const Frame F = launder(F0);
;     const int gw = F.vcu * NWAVES + F.wave, NGW = F.G * NWAVES;
;     const int co = F.lane * 4;
;     const int nfull = nrows / NGW, xr = F.wave * F.G + F.vcu, nit = nfull + (xr < nrows - nfull * NGW ? 1 : 0);
;     const bool onebatch = nfull == 4 && (NGW / 2) * 4 == SEQ; const int hw = NGW / 2;
;     ...
;     f32x4 v[8]; v2u yb[8];
;     if (nit > 0) { const int R0 = NORM_ROW(0); norm_load_x(v, xlat, xctx, xin_bf16, R0, co);
;         if (Y) {
; #pragma unroll
;             for (int j = 0; j < 8; ++j) yb[j] = *(const GAS v2u*)(Y + (size_t)R0 * DM + j * 256 + co); } }
.LBB0_1352:
	s_add_u32 s14, s0, 0x15de4000
	s_addc_u32 s15, s1, 0
	s_add_u32 s6, s6, 0x17de4000
	s_addc_u32 s7, s7, 0
	s_add_u32 s0, s8, 0x2de84000
	s_addc_u32 s1, s9, 0
	s_ashr_i32 s5, s4, 31
	v_lshlrev_b32_e32 v68, 2, v2
	s_lshl_b64 s[8:9], s[4:5], 12
	s_add_u32 s8, s0, s8
	v_ashrrev_i32_e32 v69, 31, v68
	s_addc_u32 s9, s1, s9
	v_lshlrev_b64 v[4:5], 1, v[68:69]
	v_lshl_add_u64 v[6:7], s[8:9], 0, v[4:5]
	s_add_i32 s8, s4, 0xffffe000
	s_cmpk_lt_i32 s4, 0x2000
	s_cselect_b32 s5, s5, 0
	s_cselect_b32 s4, s4, s8
	s_cselect_b32 s9, s15, s7
	s_cselect_b32 s16, s14, s6
	s_lshl_b64 s[4:5], s[4:5], 12
	s_add_u32 s4, s16, s4
	s_addc_u32 s5, s9, s5
	global_load_dwordx2 v[74:75], v[6:7], off offset:3584 nt
	global_load_dwordx2 v[76:77], v[6:7], off offset:3072 nt
	global_load_dwordx2 v[78:79], v[6:7], off offset:2560 nt
	global_load_dwordx2 v[80:81], v[6:7], off offset:2048 nt
	global_load_dwordx2 v[86:87], v[6:7], off offset:1536 nt
	global_load_dwordx2 v[100:101], v[6:7], off offset:1024 nt
	global_load_dwordx2 v[116:117], v[6:7], off offset:512 nt
	global_load_dwordx2 v[120:121], v[6:7], off nt
	v_lshl_add_u64 v[6:7], s[4:5], 0, v[4:5]
	global_load_dwordx2 v[84:85], v[6:7], off offset:3584 nt
	global_load_dwordx2 v[94:95], v[6:7], off offset:3072 nt
	global_load_dwordx2 v[98:99], v[6:7], off offset:2560 nt
	global_load_dwordx2 v[104:105], v[6:7], off offset:2048 nt
	global_load_dwordx2 v[108:109], v[6:7], off offset:1536 nt
	global_load_dwordx2 v[112:113], v[6:7], off offset:1024 nt
	global_load_dwordx2 v[114:115], v[6:7], off offset:512 nt
	global_load_dwordx2 v[118:119], v[6:7], off nt
	v_and_b32_e32 v2, 64, v224
	v_add_u32_e32 v2, 64, v2
	v_readlane_b32 s4, v254, 58
	v_lshl_add_u64 v[70:71], s[0:1], 0, v[4:5]
	v_readlane_b32 s16, v252, 0
	s_ashr_i32 s0, s13, 31
	v_readlane_b32 s1, v254, 48
	s_add_i32 s4, s10, s4
	v_lshlrev_b64 v[4:5], 2, v[68:69]
	v_readlane_b32 s18, v252, 2
	v_readlane_b32 s19, v252, 3
	s_xor_b32 s0, s0, s1
	s_abs_i32 s1, s13
	v_readlane_b32 s10, v254, 28
	v_lshl_add_u64 v[122:123], s[18:19], 0, v[4:5]
	s_mul_hi_u32 s10, s1, s10
	v_readlane_b32 s18, v254, 27
	s_mul_i32 s16, s10, s18
	v_readlane_b32 s17, v252, 1
	s_sub_i32 s1, s1, s16
	s_and_b32 s9, s13, 0x3ff
	s_add_i32 s16, s10, 1
	s_sub_i32 s17, s1, s18
	s_cmp_ge_u32 s1, s18
	s_cselect_b32 s10, s16, s10
	s_cselect_b32 s1, s17, s1
	s_add_i32 s16, s10, 1
	s_cmp_ge_u32 s1, s18
	s_cselect_b32 s1, s16, s10
	s_xor_b32 s1, s1, s0
	s_lshl_b32 s1, s1, 12
	v_lshl_add_u64 v[72:73], s[38:39], 0, v[4:5]
	s_or_b32 s1, s1, s9
	s_lshl_b32 s0, s0, 12
	v_mov_b32_e32 v4, v3
	v_mov_b32_e32 v5, v3
	v_mov_b32_e32 v10, v3
	v_mov_b32_e32 v11, v3
	v_mov_b32_e32 v12, v3
	v_mov_b32_e32 v13, v3
	v_mov_b32_e32 v14, v3
	v_mov_b32_e32 v15, v3
	v_mov_b32_e32 v16, v3
	v_mov_b32_e32 v17, v3
	v_mov_b32_e32 v18, v3
	v_mov_b32_e32 v19, v3
	v_mov_b32_e32 v20, v3
	v_mov_b32_e32 v21, v3
	v_mov_b32_e32 v22, v3
	v_mov_b32_e32 v23, v3
	v_mov_b32_e32 v24, v3
	v_mov_b32_e32 v25, v3
	v_mov_b32_e32 v26, v3
	v_mov_b32_e32 v27, v3
	v_mov_b32_e32 v28, v3
	v_mov_b32_e32 v29, v3
	v_mov_b32_e32 v30, v3
	v_mov_b32_e32 v31, v3
	v_mov_b32_e32 v32, v3
	v_mov_b32_e32 v33, v3
	s_sub_i32 s9, s1, s0
	s_bitset1_b32 s1, 10
	s_mov_b32 s5, 0
	s_mov_b32 s8, -1
	s_sub_i32 s16, s1, s0
	s_waitcnt vmcnt(0)
	v_lshlrev_b32_e32 v82, 16, v84
	v_and_b32_e32 v83, 0xffff0000, v84
	v_lshlrev_b32_e32 v84, 16, v85
	v_and_b32_e32 v85, 0xffff0000, v85
	v_lshlrev_b32_e32 v88, 16, v94
	v_and_b32_e32 v89, 0xffff0000, v94
	v_lshlrev_b32_e32 v94, 16, v95
	v_and_b32_e32 v95, 0xffff0000, v95
	v_lshlrev_b32_e32 v90, 16, v98
	v_and_b32_e32 v91, 0xffff0000, v98
	v_lshlrev_b32_e32 v98, 16, v99
	v_and_b32_e32 v99, 0xffff0000, v99
	v_lshlrev_b32_e32 v92, 16, v104
	v_and_b32_e32 v93, 0xffff0000, v104
	v_lshlrev_b32_e32 v104, 16, v105
	v_and_b32_e32 v105, 0xffff0000, v105
	v_lshlrev_b32_e32 v96, 16, v108
	v_and_b32_e32 v97, 0xffff0000, v108
	v_lshlrev_b32_e32 v108, 16, v109
	v_and_b32_e32 v109, 0xffff0000, v109
	v_lshlrev_b32_e32 v102, 16, v112
	v_and_b32_e32 v103, 0xffff0000, v112
	v_lshlrev_b32_e32 v112, 16, v113
	v_and_b32_e32 v113, 0xffff0000, v113
	v_lshlrev_b32_e32 v106, 16, v114
	v_and_b32_e32 v107, 0xffff0000, v114
	v_lshlrev_b32_e32 v114, 16, v115
	v_and_b32_e32 v115, 0xffff0000, v115
	v_mov_b32_e32 v8, v3
	v_mov_b32_e32 v9, v3
	v_lshlrev_b32_e32 v110, 16, v118
	v_and_b32_e32 v111, 0xffff0000, v118
	v_xor_b32_e32 v6, 1, v224
	v_cmp_lt_i32_e32 vcc, v6, v2
	v_lshlrev_b32_e32 v118, 16, v119
	v_and_b32_e32 v119, 0xffff0000, v119
	v_cndmask_b32_e32 v6, v224, v6, vcc
	v_lshlrev_b32_e32 v156, 2, v6
	v_xor_b32_e32 v6, 2, v224
	v_cmp_lt_i32_e32 vcc, v6, v2
	v_mov_b32_e32 v7, v3
	s_nop 0
	v_cndmask_b32_e32 v6, v224, v6, vcc
	v_lshlrev_b32_e32 v157, 2, v6
	v_xor_b32_e32 v6, 4, v224
	v_cmp_lt_i32_e32 vcc, v6, v2
	s_nop 1
	v_cndmask_b32_e32 v6, v224, v6, vcc
	v_lshlrev_b32_e32 v158, 2, v6
	v_xor_b32_e32 v6, 8, v224
	v_cmp_lt_i32_e32 vcc, v6, v2
	s_nop 1
	v_cndmask_b32_e32 v6, v224, v6, vcc
	v_lshlrev_b32_e32 v159, 2, v6
	v_xor_b32_e32 v6, 16, v224
	v_cmp_lt_i32_e32 vcc, v6, v2
	s_nop 1
	v_cndmask_b32_e32 v6, v224, v6, vcc
	v_lshlrev_b32_e32 v160, 2, v6
	v_xor_b32_e32 v6, 32, v224
	v_cmp_lt_i32_e32 vcc, v6, v2
	s_nop 1
	v_cndmask_b32_e32 v2, v224, v6, vcc
	v_mov_b32_e32 v6, v3
	v_lshlrev_b32_e32 v161, 2, v2
	v_mov_b32_e32 v2, v3
	v_mov_b64_e32 v[34:35], v[32:33]
	v_mov_b64_e32 v[32:33], v[30:31]
	v_mov_b64_e32 v[30:31], v[28:29]
	v_mov_b64_e32 v[28:29], v[26:27]
	v_mov_b64_e32 v[26:27], v[24:25]
	v_mov_b64_e32 v[24:25], v[22:23]
	v_mov_b64_e32 v[22:23], v[20:21]
	v_mov_b64_e32 v[20:21], v[18:19]
	v_mov_b64_e32 v[18:19], v[16:17]
	v_mov_b64_e32 v[16:17], v[14:15]
	v_mov_b64_e32 v[14:15], v[12:13]
	v_mov_b64_e32 v[12:13], v[10:11]
	v_mov_b64_e32 v[10:11], v[8:9]
	v_mov_b64_e32 v[8:9], v[6:7]
	v_mov_b64_e32 v[6:7], v[4:5]
	v_mov_b64_e32 v[4:5], v[2:3]
	s_branch .LBB0_1354

; #define GAS __attribute__((address_space(1)))
; DI Frame launder(const Frame& F0) { Frame F = F0; asm volatile("; launder frame" : "+v"(F.tid), "+v"(F.lane), "+s"(F.wave), "+s"(F.vcu)); return F; }
; DI void norm_load_x(f32x4 (&v)[8], const void* xlat, const void* xctx, int xin_bf16, int R, int co) {
;     if (xin_bf16) { const bf16* xr = R < NLAT ? (const bf16*)xlat + (size_t)R * DM : (const bf16*)xctx + (size_t)(R - NLAT) * DM;
;         v2u t[8];
; #pragma unroll
;         for (int j = 0; j < 8; ++j) t[j] = *(const GAS v2u*)(xr + j * 256 + co);
; #pragma unroll
;         for (int j = 0; j < 8; ++j) v[j] = (f32x4){bflo(t[j].x), bfhi(t[j].x), bflo(t[j].y), bfhi(t[j].y)}; }
;     else { const float* xr = R < NLAT ? (const float*)xlat + (size_t)R * DM : (const float*)xctx + (size_t)(R - NLAT) * DM;
; #pragma unroll
;         for (int j = 0; j < 8; ++j) v[j] = *(const GAS f32x4*)(xr + j * 256 + co); }
; }
; DI void phase_norm(const Frame& F0, int nrows, const void* xlat, const void* xctx, int xin_bf16, const bf16* Y, const float* gainY, const float* gate  ,
;                    void* Xout_lat, void* Xout_ctx, int xout_bf16, bf16* Hout, const float* gainH, const float* shift, const float* scale) {
;     const Frame F = launder(F0);
;     const int gw = F.vcu * NWAVES + F.wave, NGW = F.G * NWAVES;
;     const int co = F.lane * 4;
;     const int nfull = nrows / NGW, xr = F.wave * F.G + F.vcu, nit = nfull + (xr < nrows - nfull * NGW ? 1 : 0);
;     const bool onebatch = nfull == 4 && (NGW / 2) * 4 == SEQ; const int hw = NGW / 2;
;     ...
;     f32x4 v[8]; v2u yb[8];
;     if (nit > 0) { const int R0 = NORM_ROW(0); norm_load_x(v, xlat, xctx, xin_bf16, R0, co);
;         if (Y) {
; #pragma unroll
;             for (int j = 0; j < 8; ++j) yb[j] = *(const GAS v2u*)(Y + (size_t)R0 * DM + j * 256 + co); } }
.LBB0_1374:
	s_add_u32 s4, s4, s65
	s_addc_u32 s5, s5, 0
	s_add_u32 s12, s6, 0x15de4000
	s_addc_u32 s13, s7, 0
	s_add_u32 s16, s42, 0x17de4000
	s_addc_u32 s17, s43, 0
	s_add_u32 s6, s44, 0x2de84000
	s_addc_u32 s7, s45, 0
	s_add_u32 s18, s34, 0x15de4000
	s_addc_u32 s19, s35, 0
	s_add_u32 s24, s36, 0x17de4000
	s_addc_u32 s25, s37, 0
	s_ashr_i32 s9, s8, 31
	v_lshlrev_b32_e32 v132, 2, v2
	s_lshl_b64 s[22:23], s[8:9], 12
	s_add_u32 s22, s6, s22
	v_ashrrev_i32_e32 v133, 31, v132
	s_addc_u32 s23, s7, s23
	v_lshlrev_b64 v[4:5], 1, v[132:133]
	v_lshl_add_u64 v[6:7], s[22:23], 0, v[4:5]
	s_add_i32 s22, s8, 0xffffe000
	s_cmpk_lt_i32 s8, 0x2000
	s_cselect_b32 s9, s9, 0
	s_cselect_b32 s8, s8, s22
	s_cselect_b32 s23, s13, s17
	s_cselect_b32 s27, s12, s16
	s_lshl_b64 s[8:9], s[8:9], 12
	s_add_u32 s8, s27, s8
	s_addc_u32 s9, s23, s9
	global_load_dwordx2 v[152:153], v[6:7], off offset:3584 nt
	global_load_dwordx2 v[156:157], v[6:7], off offset:3072 nt
	global_load_dwordx2 v[160:161], v[6:7], off offset:2560 nt
	s_waitcnt lgkmcnt(0)
	global_load_dwordx2 v[162:163], v[6:7], off offset:2048 nt
	global_load_dwordx2 v[168:169], v[6:7], off offset:1536 nt
	global_load_dwordx2 v[172:173], v[6:7], off offset:1024 nt
	global_load_dwordx2 v[176:177], v[6:7], off offset:512 nt
	global_load_dwordx2 v[178:179], v[6:7], off nt
	v_lshl_add_u64 v[6:7], s[8:9], 0, v[4:5]
	global_load_dwordx2 v[146:147], v[6:7], off offset:3584 nt
	global_load_dwordx2 v[150:151], v[6:7], off offset:3072 nt
	global_load_dwordx2 v[158:159], v[6:7], off offset:2560 nt
	global_load_dwordx2 v[166:167], v[6:7], off offset:2048 nt
	global_load_dwordx2 v[174:175], v[6:7], off offset:1536 nt
	global_load_dwordx2 v[182:183], v[6:7], off offset:1024 nt
	global_load_dwordx2 v[186:187], v[6:7], off offset:512 nt
	global_load_dwordx2 v[190:191], v[6:7], off nt
	v_lshl_add_u64 v[134:135], s[6:7], 0, v[4:5]
	v_lshl_add_u64 v[4:5], s[0:1], 0, v[4:5]
	s_mov_b64 s[0:1], 0x1a1e4000
	v_and_b32_e32 v2, 64, v224
	v_lshl_add_u64 v[142:143], v[4:5], 0, s[0:1]
	v_add_u32_e32 v2, 64, v2
	v_xor_b32_e32 v4, 1, v224
	v_cmp_lt_i32_e32 vcc, v4, v2
	s_ashr_i32 s0, s15, 31
	v_readlane_b32 s1, v254, 48
	v_cndmask_b32_e32 v4, v224, v4, vcc
	v_lshlrev_b32_e32 v208, 2, v4
	v_xor_b32_e32 v4, 2, v224
	v_cmp_lt_i32_e32 vcc, v4, v2
	s_xor_b32 s0, s0, s1
	s_abs_i32 s1, s15
	v_cndmask_b32_e32 v4, v224, v4, vcc
	v_lshlrev_b32_e32 v209, 2, v4
	v_xor_b32_e32 v4, 4, v224
	v_readlane_b32 s22, v254, 27
	v_cmp_lt_i32_e32 vcc, v4, v2
	s_add_i32 s8, s10, s21
	s_and_b32 s9, s15, 0x3ff
	v_cndmask_b32_e32 v4, v224, v4, vcc
	v_lshlrev_b32_e32 v210, 2, v4
	v_xor_b32_e32 v4, 8, v224
	v_cmp_lt_i32_e32 vcc, v4, v2
	v_mov_b32_e32 v5, v3
	v_mov_b32_e32 v10, v3
	v_cndmask_b32_e32 v4, v224, v4, vcc
	v_lshlrev_b32_e32 v211, 2, v4
	v_xor_b32_e32 v4, 16, v224
	v_cmp_lt_i32_e32 vcc, v4, v2
	v_mov_b32_e32 v11, v3
	v_mov_b32_e32 v12, v3
	v_cndmask_b32_e32 v4, v224, v4, vcc
	v_lshlrev_b32_e32 v212, 2, v4
	v_xor_b32_e32 v4, 32, v224
	v_cmp_lt_i32_e32 vcc, v4, v2
	v_mov_b32_e32 v13, v3
	v_mov_b32_e32 v14, v3
	v_cndmask_b32_e32 v2, v224, v4, vcc
	v_mov_b32_e32 v4, v3
	v_mov_b32_e32 v15, v3
	v_mov_b32_e32 v16, v3
	v_mov_b32_e32 v17, v3
	v_mov_b32_e32 v18, v3
	v_mov_b32_e32 v19, v3
	v_mov_b32_e32 v20, v3
	v_mov_b32_e32 v21, v3
	v_mov_b32_e32 v22, v3
	v_mov_b32_e32 v23, v3
	v_mov_b32_e32 v24, v3
	v_mov_b32_e32 v25, v3
	v_mov_b32_e32 v26, v3
	v_mov_b32_e32 v27, v3
	v_mov_b32_e32 v28, v3
	v_mov_b32_e32 v29, v3
	v_mov_b32_e32 v30, v3
	v_mov_b32_e32 v31, v3
	v_mov_b32_e32 v32, v3
	v_mov_b32_e32 v33, v3
	v_lshlrev_b32_e32 v213, 2, v2
	v_mov_b32_e32 v2, v3
	s_mov_b32 s6, 0
	s_mov_b32 s7, -1
	s_waitcnt vmcnt(0)
	v_lshlrev_b32_e32 v144, 16, v146
	v_and_b32_e32 v145, 0xffff0000, v146
	v_lshlrev_b32_e32 v146, 16, v147
	v_and_b32_e32 v147, 0xffff0000, v147
	v_lshlrev_b32_e32 v148, 16, v150
	v_and_b32_e32 v149, 0xffff0000, v150
	v_lshlrev_b32_e32 v150, 16, v151
	v_and_b32_e32 v151, 0xffff0000, v151
	v_lshlrev_b32_e32 v154, 16, v158
	v_and_b32_e32 v155, 0xffff0000, v158
	v_lshlrev_b32_e32 v158, 16, v159
	v_and_b32_e32 v159, 0xffff0000, v159
	v_lshlrev_b32_e32 v164, 16, v166
	v_and_b32_e32 v165, 0xffff0000, v166
	v_lshlrev_b32_e32 v166, 16, v167
	v_and_b32_e32 v167, 0xffff0000, v167
	v_lshlrev_b32_e32 v170, 16, v174
	v_and_b32_e32 v171, 0xffff0000, v174
	v_lshlrev_b32_e32 v174, 16, v175
	v_and_b32_e32 v175, 0xffff0000, v175
	v_lshlrev_b32_e32 v180, 16, v182
	v_and_b32_e32 v181, 0xffff0000, v182
	v_lshlrev_b32_e32 v182, 16, v183
	v_and_b32_e32 v183, 0xffff0000, v183
	v_lshlrev_b32_e32 v184, 16, v186
	v_and_b32_e32 v185, 0xffff0000, v186
	v_lshlrev_b32_e32 v186, 16, v187
	v_and_b32_e32 v187, 0xffff0000, v187
	v_mov_b32_e32 v8, v3
	v_mov_b32_e32 v9, v3
	v_lshlrev_b32_e32 v188, 16, v190
	v_and_b32_e32 v189, 0xffff0000, v190
	v_lshlrev_b32_e32 v190, 16, v191
	v_and_b32_e32 v191, 0xffff0000, v191
	v_lshlrev_b64 v[6:7], 2, v[132:133]
	v_lshl_add_u64 v[136:137], s[38:39], 0, v[6:7]
	v_lshl_add_u64 v[6:7], s[4:5], 0, v[6:7]
	s_mov_b64 s[4:5], 0x34000
	v_lshl_add_u64 v[138:139], v[6:7], 0, s[4:5]
	s_mov_b64 s[4:5], 0x36000
	v_lshl_add_u64 v[140:141], v[6:7], 0, s[4:5]
	v_readlane_b32 s4, v254, 28
	s_mul_hi_u32 s4, s1, s4
	s_mul_i32 s5, s4, s22
	s_sub_i32 s1, s1, s5
	s_add_i32 s5, s4, 1
	s_sub_i32 s10, s1, s22
	s_cmp_ge_u32 s1, s22
	s_cselect_b32 s4, s5, s4
	s_cselect_b32 s1, s10, s1
	s_add_i32 s5, s4, 1
	s_cmp_ge_u32 s1, s22
	s_cselect_b32 s1, s5, s4
	s_xor_b32 s1, s1, s0
	s_lshl_b32 s1, s1, 12
	s_or_b32 s1, s1, s9
	s_lshl_b32 s0, s0, 12
	v_mov_b32_e32 v6, v3
	v_mov_b32_e32 v7, v3
	s_sub_i32 s9, s1, s0
	s_bitset1_b32 s1, 10
	v_mov_b64_e32 v[34:35], v[32:33]
	s_sub_i32 s28, s1, s0
	v_mov_b64_e32 v[32:33], v[30:31]
	v_mov_b64_e32 v[30:31], v[28:29]
	v_mov_b64_e32 v[28:29], v[26:27]
	v_mov_b64_e32 v[26:27], v[24:25]
	v_mov_b64_e32 v[24:25], v[22:23]
	v_mov_b64_e32 v[22:23], v[20:21]
	v_mov_b64_e32 v[20:21], v[18:19]
	v_mov_b64_e32 v[18:19], v[16:17]
	v_mov_b64_e32 v[16:17], v[14:15]
	v_mov_b64_e32 v[14:15], v[12:13]
	v_mov_b64_e32 v[12:13], v[10:11]
	v_mov_b64_e32 v[10:11], v[8:9]
	v_mov_b64_e32 v[8:9], v[6:7]
	v_mov_b64_e32 v[6:7], v[4:5]
	v_mov_b64_e32 v[4:5], v[2:3]
	s_branch .LBB0_1376
